# prologue modulation GEMV: rolling 32-deep row prefetch with SGPR-base addressing
# speedup vs baseline: 1.0016x; 1.0016x over previous
; __device__ __forceinline__ void prologue_phase(const Ctx& F, CParams& P) {
;     ...
;         for (int it = F.vcu; it < DEPTH * 192; it += F.G) {
;             const int l = it / 192, n0 = (it % 192) * 64;
;             const float* wp = P.w_mod + ((size_t)l * DM + F.wid * 256) * 12288 + n0 + F.lane;
;             float a0 = 0.f, a1 = 0.f, a2 = 0.f;
; #pragma unroll 8
;             for (int k = 0; k < 256; ++k) { const float w = wp[(size_t)k * 12288]; const int kk = F.wid * 256 + k; a0 += sv[kk] * w; a1 += sv[DM + kk] * w; a2 += sv[2 * DM + kk] * w; }
;             part[(F.wid * 3 + 0) * 64 + F.lane] = a0; part[(F.wid * 3 + 1) * 64 + F.lane] = a1; part[(F.wid * 3 + 2) * 64 + F.lane] = a2;
.LBB0_20:
	s_mul_hi_i32 s12, s36, 0x2aaaaaab
	s_lshr_b32 s13, s12, 31
	s_ashr_i32 s12, s12, 5
	s_add_i32 s14, s12, s13
	s_mul_i32 s12, s14, 0xc0
	s_sub_i32 s12, s36, s12
	s_ashr_i32 s15, s14, 31
	s_lshl_b32 s12, s12, 6
	s_lshl_b64 s[16:17], s[14:15], 11
	s_add_u32 s13, s16, s19
	s_addc_u32 s15, s17, s20
	s_mul_i32 s15, s15, 0xc000
	s_mul_hi_u32 s16, s13, 0xc000
	s_add_i32 s16, s16, s15
	s_mul_i32 s13, s13, 0xc000
	s_waitcnt lgkmcnt(0)
	s_add_u32 s15, s4, s13
	s_addc_u32 s17, s5, s16
	s_ashr_i32 s13, s12, 31
	s_lshl_b64 s[12:13], s[12:13], 2
	s_add_u32 s16, s15, s12
	s_addc_u32 s17, s17, s13
	v_mov_b32_e32 v7, 0
	s_mov_b64 s[98:99], s[16:17]
	s_mov_b64 s[100:101], s[16:17]
	s_mov_b64 s[16:17], 0
	s_mov_b32 s15, s22
	v_mov_b32_e32 v7, 0
	v_mov_b32_e32 v2, 0
	v_mov_b32_e32 v3, v7
	global_load_dword v68, v66, s[98:99]
	s_add_u32 s98, s98, 0xc000
	s_addc_u32 s99, s99, 0
	global_load_dword v70, v66, s[98:99]
	s_add_u32 s98, s98, 0xc000
	s_addc_u32 s99, s99, 0
	global_load_dword v72, v66, s[98:99]
	s_add_u32 s98, s98, 0xc000
	s_addc_u32 s99, s99, 0
	global_load_dword v74, v66, s[98:99]
	s_add_u32 s98, s98, 0xc000
	s_addc_u32 s99, s99, 0
	global_load_dword v76, v66, s[98:99]
	s_add_u32 s98, s98, 0xc000
	s_addc_u32 s99, s99, 0
	global_load_dword v78, v66, s[98:99]
	s_add_u32 s98, s98, 0xc000
	s_addc_u32 s99, s99, 0
	global_load_dword v80, v66, s[98:99]
	s_add_u32 s98, s98, 0xc000
	s_addc_u32 s99, s99, 0
	global_load_dword v82, v66, s[98:99]
	s_add_u32 s98, s98, 0xc000
	s_addc_u32 s99, s99, 0
	global_load_dword v84, v66, s[98:99]
	s_add_u32 s98, s98, 0xc000
	s_addc_u32 s99, s99, 0
	global_load_dword v86, v66, s[98:99]
	s_add_u32 s98, s98, 0xc000
	s_addc_u32 s99, s99, 0
	global_load_dword v88, v66, s[98:99]
	s_add_u32 s98, s98, 0xc000
	s_addc_u32 s99, s99, 0
	global_load_dword v90, v66, s[98:99]
	s_add_u32 s98, s98, 0xc000
	s_addc_u32 s99, s99, 0
	global_load_dword v92, v66, s[98:99]
	s_add_u32 s98, s98, 0xc000
	s_addc_u32 s99, s99, 0
	global_load_dword v94, v66, s[98:99]
	s_add_u32 s98, s98, 0xc000
	s_addc_u32 s99, s99, 0
	global_load_dword v96, v66, s[98:99]
	s_add_u32 s98, s98, 0xc000
	s_addc_u32 s99, s99, 0
	global_load_dword v98, v66, s[98:99]
	s_add_u32 s98, s98, 0xc000
	s_addc_u32 s99, s99, 0
	global_load_dword v100, v66, s[98:99]
	s_add_u32 s98, s98, 0xc000
	s_addc_u32 s99, s99, 0
	global_load_dword v102, v66, s[98:99]
	s_add_u32 s98, s98, 0xc000
	s_addc_u32 s99, s99, 0
	global_load_dword v104, v66, s[98:99]
	s_add_u32 s98, s98, 0xc000
	s_addc_u32 s99, s99, 0
	global_load_dword v106, v66, s[98:99]
	s_add_u32 s98, s98, 0xc000
	s_addc_u32 s99, s99, 0
	global_load_dword v108, v66, s[98:99]
	s_add_u32 s98, s98, 0xc000
	s_addc_u32 s99, s99, 0
	global_load_dword v110, v66, s[98:99]
	s_add_u32 s98, s98, 0xc000
	s_addc_u32 s99, s99, 0
	global_load_dword v112, v66, s[98:99]
	s_add_u32 s98, s98, 0xc000
	s_addc_u32 s99, s99, 0
	global_load_dword v114, v66, s[98:99]
	s_add_u32 s98, s98, 0xc000
	s_addc_u32 s99, s99, 0
	global_load_dword v116, v66, s[98:99]
	s_add_u32 s98, s98, 0xc000
	s_addc_u32 s99, s99, 0
	global_load_dword v118, v66, s[98:99]
	s_add_u32 s98, s98, 0xc000
	s_addc_u32 s99, s99, 0
	global_load_dword v120, v66, s[98:99]
	s_add_u32 s98, s98, 0xc000
	s_addc_u32 s99, s99, 0
	global_load_dword v122, v66, s[98:99]
	s_add_u32 s98, s98, 0xc000
	s_addc_u32 s99, s99, 0
	global_load_dword v124, v66, s[98:99]
	s_add_u32 s98, s98, 0xc000
	s_addc_u32 s99, s99, 0
	global_load_dword v126, v66, s[98:99]
	s_add_u32 s98, s98, 0xc000
	s_addc_u32 s99, s99, 0
	global_load_dword v128, v66, s[98:99]
	s_add_u32 s98, s98, 0xc000
	s_addc_u32 s99, s99, 0
	global_load_dword v130, v66, s[98:99]
	s_add_u32 s98, s98, 0xc000
	s_addc_u32 s99, s99, 0
.Lmod_k32:
	s_cmp_eq_u32 s16, 0xa80000
	s_cselect_b32 s98, s100, s98
	s_cselect_b32 s99, s101, s99
	v_mov_b32_e32 v9, s15
	s_add_i32 s15, s15, 32
	ds_read_b128 v[10:13], v9
	ds_read_b128 v[14:17], v9 offset:16
	ds_read_b128 v[18:21], v9 offset:8192
	ds_read_b128 v[22:25], v9 offset:8208
	ds_read_b128 v[26:29], v9 offset:16384
	ds_read_b128 v[30:33], v9 offset:16400
	s_waitcnt lgkmcnt(5)
	v_mov_b32_e32 v50, v10
	s_waitcnt lgkmcnt(3)
	v_mov_b32_e32 v51, v18
	v_mov_b32_e32 v18, v11
	v_mov_b32_e32 v10, v12
	v_mov_b32_e32 v11, v20
	v_mov_b32_e32 v20, v13
	v_mov_b32_e32 v12, v14
	s_waitcnt lgkmcnt(2)
	v_mov_b32_e32 v13, v22
	v_mov_b32_e32 v22, v15
	v_mov_b32_e32 v14, v16
	v_mov_b32_e32 v15, v24
	v_mov_b32_e32 v24, v17
	s_waitcnt vmcnt(31)
	v_pk_fma_f32 v[2:3], v[68:69], v[50:51], v[2:3] op_sel_hi:[0,1,1]
	s_waitcnt lgkmcnt(1)
	v_fmac_f32_e32 v7, v68, v26
	s_waitcnt vmcnt(30)
	v_pk_fma_f32 v[2:3], v[70:71], v[18:19], v[2:3] op_sel_hi:[0,1,1]
	v_fmac_f32_e32 v7, v70, v27
	s_waitcnt vmcnt(29)
	v_pk_fma_f32 v[2:3], v[72:73], v[10:11], v[2:3] op_sel_hi:[0,1,1]
	v_fmac_f32_e32 v7, v72, v28
	s_waitcnt vmcnt(28)
	v_pk_fma_f32 v[2:3], v[74:75], v[20:21], v[2:3] op_sel_hi:[0,1,1]
	v_fmac_f32_e32 v7, v74, v29
	s_waitcnt vmcnt(27)
	v_pk_fma_f32 v[2:3], v[76:77], v[12:13], v[2:3] op_sel_hi:[0,1,1]
	s_waitcnt lgkmcnt(0)
	v_fmac_f32_e32 v7, v76, v30
	s_waitcnt vmcnt(26)
	v_pk_fma_f32 v[2:3], v[78:79], v[22:23], v[2:3] op_sel_hi:[0,1,1]
	v_fmac_f32_e32 v7, v78, v31
	s_waitcnt vmcnt(25)
	v_pk_fma_f32 v[2:3], v[80:81], v[14:15], v[2:3] op_sel_hi:[0,1,1]
	v_fmac_f32_e32 v7, v80, v32
	s_waitcnt vmcnt(24)
; __device__ __forceinline__ void prologue_phase(const Ctx& F, CParams& P) {
;     ...
;         for (int it = F.vcu; it < DEPTH * 192; it += F.G) {
;             const int l = it / 192, n0 = (it % 192) * 64;
;             const float* wp = P.w_mod + ((size_t)l * DM + F.wid * 256) * 12288 + n0 + F.lane;
;             float a0 = 0.f, a1 = 0.f, a2 = 0.f;
; #pragma unroll 8
;             for (int k = 0; k < 256; ++k) { const float w = wp[(size_t)k * 12288]; const int kk = F.wid * 256 + k; a0 += sv[kk] * w; a1 += sv[DM + kk] * w; a2 += sv[2 * DM + kk] * w; }
;             part[(F.wid * 3 + 0) * 64 + F.lane] = a0; part[(F.wid * 3 + 1) * 64 + F.lane] = a1; part[(F.wid * 3 + 2) * 64 + F.lane] = a2;
	v_pk_fma_f32 v[2:3], v[82:83], v[24:25], v[2:3] op_sel_hi:[0,1,1]
	v_fmac_f32_e32 v7, v82, v33
	global_load_dword v68, v66, s[98:99]
	s_add_u32 s98, s98, 0xc000
	s_addc_u32 s99, s99, 0
	global_load_dword v70, v66, s[98:99]
	s_add_u32 s98, s98, 0xc000
	s_addc_u32 s99, s99, 0
	global_load_dword v72, v66, s[98:99]
	s_add_u32 s98, s98, 0xc000
	s_addc_u32 s99, s99, 0
	global_load_dword v74, v66, s[98:99]
	s_add_u32 s98, s98, 0xc000
	s_addc_u32 s99, s99, 0
	global_load_dword v76, v66, s[98:99]
	s_add_u32 s98, s98, 0xc000
	s_addc_u32 s99, s99, 0
	global_load_dword v78, v66, s[98:99]
	s_add_u32 s98, s98, 0xc000
	s_addc_u32 s99, s99, 0
	global_load_dword v80, v66, s[98:99]
	s_add_u32 s98, s98, 0xc000
	s_addc_u32 s99, s99, 0
	global_load_dword v82, v66, s[98:99]
	s_add_u32 s98, s98, 0xc000
	s_addc_u32 s99, s99, 0
	v_mov_b32_e32 v9, s15
	s_add_i32 s15, s15, 32
	ds_read_b128 v[10:13], v9
	ds_read_b128 v[14:17], v9 offset:16
	ds_read_b128 v[18:21], v9 offset:8192
	ds_read_b128 v[22:25], v9 offset:8208
	ds_read_b128 v[26:29], v9 offset:16384
	ds_read_b128 v[30:33], v9 offset:16400
	s_waitcnt lgkmcnt(5)
	v_mov_b32_e32 v50, v10
	s_waitcnt lgkmcnt(3)
	v_mov_b32_e32 v51, v18
	v_mov_b32_e32 v18, v11
	v_mov_b32_e32 v10, v12
	v_mov_b32_e32 v11, v20
	v_mov_b32_e32 v20, v13
	v_mov_b32_e32 v12, v14
	s_waitcnt lgkmcnt(2)
	v_mov_b32_e32 v13, v22
	v_mov_b32_e32 v22, v15
	v_mov_b32_e32 v14, v16
	v_mov_b32_e32 v15, v24
	v_mov_b32_e32 v24, v17
	s_waitcnt vmcnt(31)
	v_pk_fma_f32 v[2:3], v[84:85], v[50:51], v[2:3] op_sel_hi:[0,1,1]
	s_waitcnt lgkmcnt(1)
	v_fmac_f32_e32 v7, v84, v26
	s_waitcnt vmcnt(30)
	v_pk_fma_f32 v[2:3], v[86:87], v[18:19], v[2:3] op_sel_hi:[0,1,1]
	v_fmac_f32_e32 v7, v86, v27
	s_waitcnt vmcnt(29)
	v_pk_fma_f32 v[2:3], v[88:89], v[10:11], v[2:3] op_sel_hi:[0,1,1]
	v_fmac_f32_e32 v7, v88, v28
	s_waitcnt vmcnt(28)
	v_pk_fma_f32 v[2:3], v[90:91], v[20:21], v[2:3] op_sel_hi:[0,1,1]
	v_fmac_f32_e32 v7, v90, v29
	s_waitcnt vmcnt(27)
	v_pk_fma_f32 v[2:3], v[92:93], v[12:13], v[2:3] op_sel_hi:[0,1,1]
	s_waitcnt lgkmcnt(0)
	v_fmac_f32_e32 v7, v92, v30
	s_waitcnt vmcnt(26)
	v_pk_fma_f32 v[2:3], v[94:95], v[22:23], v[2:3] op_sel_hi:[0,1,1]
	v_fmac_f32_e32 v7, v94, v31
	s_waitcnt vmcnt(25)
	v_pk_fma_f32 v[2:3], v[96:97], v[14:15], v[2:3] op_sel_hi:[0,1,1]
	v_fmac_f32_e32 v7, v96, v32
	s_waitcnt vmcnt(24)
	v_pk_fma_f32 v[2:3], v[98:99], v[24:25], v[2:3] op_sel_hi:[0,1,1]
	v_fmac_f32_e32 v7, v98, v33
	global_load_dword v84, v66, s[98:99]
	s_add_u32 s98, s98, 0xc000
	s_addc_u32 s99, s99, 0
	global_load_dword v86, v66, s[98:99]
	s_add_u32 s98, s98, 0xc000
	s_addc_u32 s99, s99, 0
	global_load_dword v88, v66, s[98:99]
	s_add_u32 s98, s98, 0xc000
	s_addc_u32 s99, s99, 0
	global_load_dword v90, v66, s[98:99]
	s_add_u32 s98, s98, 0xc000
	s_addc_u32 s99, s99, 0
	global_load_dword v92, v66, s[98:99]
	s_add_u32 s98, s98, 0xc000
	s_addc_u32 s99, s99, 0
	global_load_dword v94, v66, s[98:99]
	s_add_u32 s98, s98, 0xc000
	s_addc_u32 s99, s99, 0
	global_load_dword v96, v66, s[98:99]
	s_add_u32 s98, s98, 0xc000
	s_addc_u32 s99, s99, 0
	global_load_dword v98, v66, s[98:99]
	s_add_u32 s98, s98, 0xc000
	s_addc_u32 s99, s99, 0
	v_mov_b32_e32 v9, s15
	s_add_i32 s15, s15, 32
	ds_read_b128 v[10:13], v9
	ds_read_b128 v[14:17], v9 offset:16
	ds_read_b128 v[18:21], v9 offset:8192
	ds_read_b128 v[22:25], v9 offset:8208
	ds_read_b128 v[26:29], v9 offset:16384
	ds_read_b128 v[30:33], v9 offset:16400
	s_waitcnt lgkmcnt(5)
	v_mov_b32_e32 v50, v10
	s_waitcnt lgkmcnt(3)
	v_mov_b32_e32 v51, v18
	v_mov_b32_e32 v18, v11
	v_mov_b32_e32 v10, v12
	v_mov_b32_e32 v11, v20
	v_mov_b32_e32 v20, v13
	v_mov_b32_e32 v12, v14
	s_waitcnt lgkmcnt(2)
	v_mov_b32_e32 v13, v22
	v_mov_b32_e32 v22, v15
	v_mov_b32_e32 v14, v16
	v_mov_b32_e32 v15, v24
	v_mov_b32_e32 v24, v17
	s_waitcnt vmcnt(31)
	v_pk_fma_f32 v[2:3], v[100:101], v[50:51], v[2:3] op_sel_hi:[0,1,1]
	s_waitcnt lgkmcnt(1)
	v_fmac_f32_e32 v7, v100, v26
	s_waitcnt vmcnt(30)
	v_pk_fma_f32 v[2:3], v[102:103], v[18:19], v[2:3] op_sel_hi:[0,1,1]
	v_fmac_f32_e32 v7, v102, v27
	s_waitcnt vmcnt(29)
	v_pk_fma_f32 v[2:3], v[104:105], v[10:11], v[2:3] op_sel_hi:[0,1,1]
	v_fmac_f32_e32 v7, v104, v28
	s_waitcnt vmcnt(28)
	v_pk_fma_f32 v[2:3], v[106:107], v[20:21], v[2:3] op_sel_hi:[0,1,1]
	v_fmac_f32_e32 v7, v106, v29
	s_waitcnt vmcnt(27)
	v_pk_fma_f32 v[2:3], v[108:109], v[12:13], v[2:3] op_sel_hi:[0,1,1]
	s_waitcnt lgkmcnt(0)
	v_fmac_f32_e32 v7, v108, v30
	s_waitcnt vmcnt(26)
	v_pk_fma_f32 v[2:3], v[110:111], v[22:23], v[2:3] op_sel_hi:[0,1,1]
	v_fmac_f32_e32 v7, v110, v31
	s_waitcnt vmcnt(25)
	v_pk_fma_f32 v[2:3], v[112:113], v[14:15], v[2:3] op_sel_hi:[0,1,1]
	v_fmac_f32_e32 v7, v112, v32
	s_waitcnt vmcnt(24)
; __device__ __forceinline__ void prologue_phase(const Ctx& F, CParams& P) {
;     ...
;         for (int it = F.vcu; it < DEPTH * 192; it += F.G) {
;             const int l = it / 192, n0 = (it % 192) * 64;
;             const float* wp = P.w_mod + ((size_t)l * DM + F.wid * 256) * 12288 + n0 + F.lane;
;             float a0 = 0.f, a1 = 0.f, a2 = 0.f;
; #pragma unroll 8
;             for (int k = 0; k < 256; ++k) { const float w = wp[(size_t)k * 12288]; const int kk = F.wid * 256 + k; a0 += sv[kk] * w; a1 += sv[DM + kk] * w; a2 += sv[2 * DM + kk] * w; }
;             part[(F.wid * 3 + 0) * 64 + F.lane] = a0; part[(F.wid * 3 + 1) * 64 + F.lane] = a1; part[(F.wid * 3 + 2) * 64 + F.lane] = a2;
;             __syncthreads();
;             if (F.wid < 3) { float s = 0.f;
; #pragma unroll
;                 for (int w = 0; w < 8; ++w) s += part[(w * 3 + F.wid) * 64 + F.lane];
;                 mod[((size_t)l * 3 + F.wid) * 12288 + n0 + F.lane] = s + P.b_mod[(size_t)l * 12288 + n0 + F.lane]; }
;             __syncthreads();
	v_pk_fma_f32 v[2:3], v[114:115], v[24:25], v[2:3] op_sel_hi:[0,1,1]
	v_fmac_f32_e32 v7, v114, v33
	global_load_dword v100, v66, s[98:99]
	s_add_u32 s98, s98, 0xc000
	s_addc_u32 s99, s99, 0
	global_load_dword v102, v66, s[98:99]
	s_add_u32 s98, s98, 0xc000
	s_addc_u32 s99, s99, 0
	global_load_dword v104, v66, s[98:99]
	s_add_u32 s98, s98, 0xc000
	s_addc_u32 s99, s99, 0
	global_load_dword v106, v66, s[98:99]
	s_add_u32 s98, s98, 0xc000
	s_addc_u32 s99, s99, 0
	global_load_dword v108, v66, s[98:99]
	s_add_u32 s98, s98, 0xc000
	s_addc_u32 s99, s99, 0
	global_load_dword v110, v66, s[98:99]
	s_add_u32 s98, s98, 0xc000
	s_addc_u32 s99, s99, 0
	global_load_dword v112, v66, s[98:99]
	s_add_u32 s98, s98, 0xc000
	s_addc_u32 s99, s99, 0
	global_load_dword v114, v66, s[98:99]
	s_add_u32 s98, s98, 0xc000
	s_addc_u32 s99, s99, 0
	v_mov_b32_e32 v9, s15
	s_add_i32 s15, s15, 32
	ds_read_b128 v[10:13], v9
	ds_read_b128 v[14:17], v9 offset:16
	ds_read_b128 v[18:21], v9 offset:8192
	ds_read_b128 v[22:25], v9 offset:8208
	ds_read_b128 v[26:29], v9 offset:16384
	ds_read_b128 v[30:33], v9 offset:16400
	s_waitcnt lgkmcnt(5)
	v_mov_b32_e32 v50, v10
	s_waitcnt lgkmcnt(3)
	v_mov_b32_e32 v51, v18
	v_mov_b32_e32 v18, v11
	v_mov_b32_e32 v10, v12
	v_mov_b32_e32 v11, v20
	v_mov_b32_e32 v20, v13
	v_mov_b32_e32 v12, v14
	s_waitcnt lgkmcnt(2)
	v_mov_b32_e32 v13, v22
	v_mov_b32_e32 v22, v15
	v_mov_b32_e32 v14, v16
	v_mov_b32_e32 v15, v24
	v_mov_b32_e32 v24, v17
	s_waitcnt vmcnt(31)
	v_pk_fma_f32 v[2:3], v[116:117], v[50:51], v[2:3] op_sel_hi:[0,1,1]
	s_waitcnt lgkmcnt(1)
	v_fmac_f32_e32 v7, v116, v26
	s_waitcnt vmcnt(30)
	v_pk_fma_f32 v[2:3], v[118:119], v[18:19], v[2:3] op_sel_hi:[0,1,1]
	v_fmac_f32_e32 v7, v118, v27
	s_waitcnt vmcnt(29)
	v_pk_fma_f32 v[2:3], v[120:121], v[10:11], v[2:3] op_sel_hi:[0,1,1]
	v_fmac_f32_e32 v7, v120, v28
	s_waitcnt vmcnt(28)
	v_pk_fma_f32 v[2:3], v[122:123], v[20:21], v[2:3] op_sel_hi:[0,1,1]
	v_fmac_f32_e32 v7, v122, v29
	s_waitcnt vmcnt(27)
	v_pk_fma_f32 v[2:3], v[124:125], v[12:13], v[2:3] op_sel_hi:[0,1,1]
	s_waitcnt lgkmcnt(0)
	v_fmac_f32_e32 v7, v124, v30
	s_waitcnt vmcnt(26)
	v_pk_fma_f32 v[2:3], v[126:127], v[22:23], v[2:3] op_sel_hi:[0,1,1]
	v_fmac_f32_e32 v7, v126, v31
	s_waitcnt vmcnt(25)
	v_pk_fma_f32 v[2:3], v[128:129], v[14:15], v[2:3] op_sel_hi:[0,1,1]
	v_fmac_f32_e32 v7, v128, v32
	s_waitcnt vmcnt(24)
	v_pk_fma_f32 v[2:3], v[130:131], v[24:25], v[2:3] op_sel_hi:[0,1,1]
	v_fmac_f32_e32 v7, v130, v33
	global_load_dword v116, v66, s[98:99]
	s_add_u32 s98, s98, 0xc000
	s_addc_u32 s99, s99, 0
	global_load_dword v118, v66, s[98:99]
	s_add_u32 s98, s98, 0xc000
	s_addc_u32 s99, s99, 0
	global_load_dword v120, v66, s[98:99]
	s_add_u32 s98, s98, 0xc000
	s_addc_u32 s99, s99, 0
	global_load_dword v122, v66, s[98:99]
	s_add_u32 s98, s98, 0xc000
	s_addc_u32 s99, s99, 0
	global_load_dword v124, v66, s[98:99]
	s_add_u32 s98, s98, 0xc000
	s_addc_u32 s99, s99, 0
	global_load_dword v126, v66, s[98:99]
	s_add_u32 s98, s98, 0xc000
	s_addc_u32 s99, s99, 0
	global_load_dword v128, v66, s[98:99]
	s_add_u32 s98, s98, 0xc000
	s_addc_u32 s99, s99, 0
	global_load_dword v130, v66, s[98:99]
	s_add_u32 s98, s98, 0xc000
	s_addc_u32 s99, s99, 0
	s_add_u32 s16, s16, 0x180000
	s_cmp_eq_u32 s16, 0xc00000
	s_cbranch_scc0 .Lmod_k32
	s_waitcnt vmcnt(0)
	s_and_b64 vcc, exec, s[2:3]
	ds_write_b32 v4, v2 offset:24576
	ds_write2st64_b32 v5, v3, v7 offset0:97 offset1:98
	s_waitcnt lgkmcnt(0)
	s_barrier
	s_cbranch_vccnz .LBB0_19
	s_mul_i32 s16, s14, 0xc000
	s_mul_hi_i32 s15, s14, 0xc000
	s_add_u32 s16, s6, s16
	s_addc_u32 s15, s7, s15
	s_add_u32 s16, s16, s12
	s_addc_u32 s17, s15, s13
	v_lshlrev_b64 v[0:1], 2, v[64:65]
	v_lshl_add_u64 v[2:3], s[16:17], 0, v[0:1]
	global_load_dword v7, v[2:3], off
	ds_read2st64_b32 v[2:3], v6 offset0:96 offset1:99
	ds_read2st64_b32 v[10:11], v6 offset0:102 offset1:105
	ds_read2st64_b32 v[12:13], v6 offset0:108 offset1:111
	ds_read2st64_b32 v[14:15], v6 offset0:114 offset1:117
	s_mul_hi_i32 s15, s14, 3
	s_mul_i32 s14, s14, 3
	s_waitcnt lgkmcnt(3)
	v_add_f32_e32 v2, 0, v2
	s_add_u32 s14, s14, s30
	v_add_f32_e32 v2, v2, v3
	s_addc_u32 s15, s15, s21
	s_mul_hi_u32 s16, s14, 0xc000
	s_waitcnt lgkmcnt(2)
	v_add_f32_e32 v2, v2, v10
	s_mul_i32 s15, s15, 0xc000
	s_mul_i32 s14, s14, 0xc000
	v_add_f32_e32 v2, v2, v11
	s_add_i32 s16, s16, s15
	s_waitcnt lgkmcnt(1)
	v_add_f32_e32 v2, v2, v12
	s_add_u32 s14, s9, s14
	v_add_f32_e32 v2, v2, v13
	s_addc_u32 s15, s18, s16
	s_waitcnt lgkmcnt(0)
	v_add_f32_e32 v2, v2, v14
	s_add_u32 s12, s14, s12
	v_add_f32_e32 v2, v2, v15
	s_addc_u32 s13, s15, s13
	v_lshl_add_u64 v[0:1], s[12:13], 0, v[0:1]
	s_waitcnt vmcnt(0)
	v_add_f32_e32 v2, v2, v7
	global_store_dword v[0:1], v2, off
	s_branch .LBB0_19
